# v6_ntmid
# speedup vs baseline: 1.0196x; 1.0196x over previous
; __device__ __forceinline__ float bf_lo(unsigned w) { return __uint_as_float(w << 16); }
; __device__ __forceinline__ float bf_hi(unsigned w) { return __uint_as_float(w & 0xffff0000u); }
; __device__ __forceinline__ float wave_sum(float v) {
; #pragma unroll
;     for (int o = 1; o < 64; o <<= 1) v += __shfl_xor(v, o);
;     return v;
; __device__ __forceinline__ void phase_mid(const Params& p, int gw, int NGW, int lane) {
;     ...
;     for (int row = gw; row < MT; row += NGW) {
;         const float r1 = rsqrtf(wave_sum(SSQ[(size_t)lane * MT + row]) * (1.f / DM) + EPSN);
;         const u32x2* mr = (const u32x2*)(MO + (size_t)row * DM) + lane; const f32x4* xr = (const f32x4*)(x + (size_t)row * DM) + lane;
;         const f32x4* g1p = g1 + lane; const f32x4* g2p = g2 + lane;
;         asm volatile("" : "+v"(g1p), "+v"(g2p), "+v"(mr), "+v"(xr));
;         f32x4 h[16]; float ss = 0.f;
; #pragma unroll
;         for (int j = 0; j < 16; ++j) { const u32x2 mw = mr[64 * j]; const f32x4 mo = {bf_lo(mw.x), bf_hi(mw.x), bf_lo(mw.y), bf_hi(mw.y)}; h[j] = xr[64 * j] + mo * r1 * g1p[64 * j]; ss += (h[j][0] * h[j][0] + h[j][1] * h[j][1]) + (h[j][2] * h[j][2] + h[j][3] * h[j][3]); }
.LBB0_711:
	global_load_dword v26, v[10:11], off
	v_lshl_add_u64 v[20:21], v[0:1], 0, s[6:7]
	v_mov_b64_e32 v[14:15], v[4:5]
	v_mov_b64_e32 v[18:19], v[12:13]
	v_mov_b64_e32 v[16:17], v[2:3]
	flat_load_dwordx4 v[28:31], v[18:19] nt
	flat_load_dwordx4 v[32:35], v[18:19] offset:1024 nt
	flat_load_dwordx4 v[36:39], v[16:17]
	flat_load_dwordx4 v[40:43], v[16:17] offset:1024
	flat_load_dwordx2 v[66:67], v[20:21] nt
	flat_load_dwordx2 v[68:69], v[20:21] offset:512 nt
	flat_load_dwordx2 v[70:71], v[20:21] offset:1024 nt
	flat_load_dwordx2 v[72:73], v[20:21] offset:1536 nt
	flat_load_dwordx4 v[46:49], v[18:19] offset:2048 nt
	flat_load_dwordx4 v[50:53], v[18:19] offset:3072 nt
	flat_load_dwordx4 v[54:57], v[16:17] offset:2048
	flat_load_dwordx4 v[58:61], v[16:17] offset:3072
	v_add_co_u32_e32 v92, vcc, s9, v18
	flat_load_dwordx2 v[168:169], v[20:21] offset:2048 nt
	flat_load_dwordx2 v[170:171], v[20:21] offset:2560 nt
	flat_load_dwordx2 v[172:173], v[20:21] offset:3072 nt
	flat_load_dwordx2 v[180:181], v[20:21] offset:3584 nt
	v_addc_co_u32_e32 v93, vcc, 0, v19, vcc
	v_add_co_u32_e32 v100, vcc, s9, v16
	v_lshl_add_u64 v[24:25], v[6:7], 0, s[6:7]
	s_nop 0
	v_addc_co_u32_e32 v101, vcc, 0, v17, vcc
	v_add_co_u32_e32 v20, vcc, s9, v20
	v_lshl_add_u64 v[22:23], v[8:9], 0, s[6:7]
	s_nop 0
	v_addc_co_u32_e32 v21, vcc, 0, v21, vcc
	v_add_co_u32_e32 v124, vcc, s3, v18
	s_add_i32 s17, s17, s60
	s_nop 0
	v_addc_co_u32_e32 v125, vcc, 0, v19, vcc
	v_add_co_u32_e32 v132, vcc, s3, v16
	s_add_u32 s6, s6, s12
	s_nop 0
	v_addc_co_u32_e32 v133, vcc, 0, v17, vcc
	v_add_co_u32_e32 v156, vcc, s16, v18
	s_addc_u32 s7, s7, s13
	s_nop 0
	v_addc_co_u32_e32 v157, vcc, 0, v19, vcc
	v_add_co_u32_e32 v164, vcc, s16, v16
	v_lshl_add_u64 v[10:11], v[10:11], 0, s[4:5]
	s_nop 0
	v_addc_co_u32_e32 v165, vcc, 0, v17, vcc
	flat_load_dwordx2 v[182:183], v[20:21] nt
	flat_load_dwordx2 v[184:185], v[20:21] offset:512 nt
	flat_load_dwordx2 v[186:187], v[20:21] offset:1024 nt
	flat_load_dwordx2 v[188:189], v[20:21] offset:1536 nt
	flat_load_dwordx2 v[190:191], v[20:21] offset:2048 nt
	flat_load_dwordx2 v[194:195], v[20:21] offset:2560 nt
	flat_load_dwordx4 v[16:19], v[92:93] nt
	flat_load_dwordx4 v[80:83], v[92:93] offset:1024 nt
	flat_load_dwordx4 v[62:65], v[100:101]
	flat_load_dwordx4 v[84:87], v[100:101] offset:1024
	flat_load_dwordx2 v[196:197], v[20:21] offset:3072 nt
	flat_load_dwordx4 v[88:91], v[92:93] offset:2048 nt
	s_nop 0
	flat_load_dwordx4 v[92:95], v[92:93] offset:3072 nt
	s_nop 0
	flat_load_dwordx2 v[20:21], v[20:21] offset:3584 nt
	s_nop 0
	flat_load_dwordx4 v[96:99], v[100:101] offset:2048
	s_nop 0
	flat_load_dwordx4 v[100:103], v[100:101] offset:3072
	s_nop 0
	flat_load_dwordx4 v[104:107], v[124:125] nt
	flat_load_dwordx4 v[108:111], v[124:125] offset:1024 nt
	flat_load_dwordx4 v[112:115], v[132:133]
	flat_load_dwordx4 v[116:119], v[132:133] offset:1024
	flat_load_dwordx4 v[120:123], v[124:125] offset:2048 nt
	s_nop 0
	flat_load_dwordx4 v[124:127], v[124:125] offset:3072 nt
	s_nop 0
	flat_load_dwordx4 v[128:131], v[132:133] offset:2048
	s_nop 0
	flat_load_dwordx4 v[132:135], v[132:133] offset:3072
	s_nop 0
	flat_load_dwordx4 v[136:139], v[156:157] nt
	flat_load_dwordx4 v[140:143], v[156:157] offset:1024 nt
	flat_load_dwordx4 v[144:147], v[164:165]
	flat_load_dwordx4 v[148:151], v[164:165] offset:1024
	flat_load_dwordx4 v[152:155], v[156:157] offset:2048 nt
	s_nop 0
	flat_load_dwordx4 v[156:159], v[156:157] offset:3072 nt
	s_nop 0
	flat_load_dwordx4 v[160:163], v[164:165] offset:2048
	s_nop 0
	flat_load_dwordx4 v[164:167], v[164:165] offset:3072
	v_lshl_add_u64 v[12:13], v[12:13], 0, s[14:15]
	s_cmpk_lt_i32 s17, 0x2000
	s_waitcnt vmcnt(0) lgkmcnt(0)
	v_lshlrev_b32_e32 v198, 16, v66
	ds_bpermute_b32 v27, v45, v26
	v_and_b32_e32 v199, 0xffff0000, v66
	v_lshlrev_b32_e32 v66, 16, v67
	v_and_b32_e32 v67, 0xffff0000, v67
	v_lshlrev_b32_e32 v200, 16, v68
	s_waitcnt lgkmcnt(0)
	v_add_f32_e32 v26, v26, v27
	ds_bpermute_b32 v27, v74, v26
	v_and_b32_e32 v201, 0xffff0000, v68
	v_lshlrev_b32_e32 v68, 16, v69
	v_and_b32_e32 v69, 0xffff0000, v69
	v_lshlrev_b32_e32 v202, 16, v70
	s_waitcnt lgkmcnt(0)
	v_add_f32_e32 v26, v26, v27
	ds_bpermute_b32 v27, v75, v26
	v_and_b32_e32 v203, 0xffff0000, v70
	v_lshlrev_b32_e32 v70, 16, v71
	v_and_b32_e32 v71, 0xffff0000, v71
	v_lshlrev_b32_e32 v204, 16, v72
	s_waitcnt lgkmcnt(0)
	v_add_f32_e32 v26, v26, v27
	ds_bpermute_b32 v27, v76, v26
	v_and_b32_e32 v205, 0xffff0000, v72
	v_lshlrev_b32_e32 v72, 16, v73
	v_and_b32_e32 v73, 0xffff0000, v73
	v_lshlrev_b32_e32 v206, 16, v168
	s_waitcnt lgkmcnt(0)
	v_add_f32_e32 v26, v26, v27
	ds_bpermute_b32 v27, v77, v26
	v_and_b32_e32 v207, 0xffff0000, v168
	v_lshlrev_b32_e32 v168, 16, v169
	v_and_b32_e32 v169, 0xffff0000, v169
	v_lshlrev_b32_e32 v208, 16, v170
	s_waitcnt lgkmcnt(0)
	v_add_f32_e32 v26, v26, v27
	ds_bpermute_b32 v27, v78, v26
	v_and_b32_e32 v209, 0xffff0000, v170
	v_lshlrev_b32_e32 v170, 16, v171
	v_and_b32_e32 v171, 0xffff0000, v171
	v_lshlrev_b32_e32 v212, 16, v180
	s_waitcnt lgkmcnt(0)
; __device__ __forceinline__ float bf_lo(unsigned w) { return __uint_as_float(w << 16); }
; __device__ __forceinline__ float bf_hi(unsigned w) { return __uint_as_float(w & 0xffff0000u); }
; __device__ __forceinline__ void phase_mid(const Params& p, int gw, int NGW, int lane) {
;     ...
;         const float r1 = rsqrtf(wave_sum(SSQ[(size_t)lane * MT + row]) * (1.f / DM) + EPSN);
;         const u32x2* mr = (const u32x2*)(MO + (size_t)row * DM) + lane; const f32x4* xr = (const f32x4*)(x + (size_t)row * DM) + lane;
;         const f32x4* g1p = g1 + lane; const f32x4* g2p = g2 + lane;
;         asm volatile("" : "+v"(g1p), "+v"(g2p), "+v"(mr), "+v"(xr));
;         f32x4 h[16]; float ss = 0.f;
; #pragma unroll
;         for (int j = 0; j < 16; ++j) { const u32x2 mw = mr[64 * j]; const f32x4 mo = {bf_lo(mw.x), bf_hi(mw.x), bf_lo(mw.y), bf_hi(mw.y)}; h[j] = xr[64 * j] + mo * r1 * g1p[64 * j]; ss += (h[j][0] * h[j][0] + h[j][1] * h[j][1]) + (h[j][2] * h[j][2] + h[j][3] * h[j][3]); }
	v_add_f32_e32 v26, v26, v27
	v_fmamk_f32 v26, v26, 0x39800000, v79
	v_mul_f32_e32 v27, 0x4b800000, v26
	v_cmp_gt_f32_e32 vcc, s8, v26
	v_and_b32_e32 v213, 0xffff0000, v180
	v_lshlrev_b32_e32 v180, 16, v181
	v_cndmask_b32_e32 v26, v26, v27, vcc
	v_rsq_f32_e32 v26, v26
	v_and_b32_e32 v181, 0xffff0000, v181
	v_lshlrev_b32_e32 v214, 16, v182
	v_and_b32_e32 v215, 0xffff0000, v182
	v_mul_f32_e32 v27, 0x45800000, v26
	v_cndmask_b32_e32 v26, v26, v27, vcc
	v_lshlrev_b32_e32 v182, 16, v183
	v_and_b32_e32 v183, 0xffff0000, v183
	v_lshlrev_b32_e32 v218, 16, v186
	v_and_b32_e32 v219, 0xffff0000, v186
	v_lshlrev_b32_e32 v186, 16, v187
	v_and_b32_e32 v187, 0xffff0000, v187
	v_lshlrev_b32_e32 v220, 16, v188
	v_and_b32_e32 v221, 0xffff0000, v188
	v_lshlrev_b32_e32 v188, 16, v189
	v_and_b32_e32 v189, 0xffff0000, v189
	v_lshlrev_b32_e32 v224, 16, v194
	v_and_b32_e32 v225, 0xffff0000, v194
	v_lshlrev_b32_e32 v194, 16, v195
	v_and_b32_e32 v195, 0xffff0000, v195
	v_lshlrev_b32_e32 v226, 16, v196
	v_and_b32_e32 v227, 0xffff0000, v196
	v_lshlrev_b32_e32 v196, 16, v197
	v_and_b32_e32 v197, 0xffff0000, v197
	v_pk_mul_f32 v[198:199], v[26:27], v[198:199] op_sel_hi:[0,1]
	v_pk_mul_f32 v[66:67], v[26:27], v[66:67] op_sel_hi:[0,1]
	v_pk_mul_f32 v[200:201], v[26:27], v[200:201] op_sel_hi:[0,1]
	v_pk_mul_f32 v[68:69], v[26:27], v[68:69] op_sel_hi:[0,1]
	v_lshlrev_b32_e32 v210, 16, v172
	v_and_b32_e32 v211, 0xffff0000, v172
	v_lshlrev_b32_e32 v172, 16, v173
	v_and_b32_e32 v173, 0xffff0000, v173
	v_lshlrev_b32_e32 v216, 16, v184
	v_and_b32_e32 v217, 0xffff0000, v184
	v_lshlrev_b32_e32 v184, 16, v185
	v_and_b32_e32 v185, 0xffff0000, v185
	v_lshlrev_b32_e32 v222, 16, v190
	v_and_b32_e32 v223, 0xffff0000, v190
	v_lshlrev_b32_e32 v190, 16, v191
	v_and_b32_e32 v191, 0xffff0000, v191
	v_lshlrev_b32_e32 v228, 16, v20
	v_and_b32_e32 v229, 0xffff0000, v20
	v_lshlrev_b32_e32 v20, 16, v21
	v_and_b32_e32 v21, 0xffff0000, v21
	v_pk_mul_f32 v[202:203], v[26:27], v[202:203] op_sel_hi:[0,1]
	v_pk_mul_f32 v[70:71], v[26:27], v[70:71] op_sel_hi:[0,1]
	v_pk_mul_f32 v[204:205], v[26:27], v[204:205] op_sel_hi:[0,1]
	v_pk_mul_f32 v[72:73], v[26:27], v[72:73] op_sel_hi:[0,1]
	v_pk_mul_f32 v[206:207], v[26:27], v[206:207] op_sel_hi:[0,1]
	v_pk_mul_f32 v[168:169], v[26:27], v[168:169] op_sel_hi:[0,1]
	v_pk_mul_f32 v[208:209], v[26:27], v[208:209] op_sel_hi:[0,1]
	v_pk_mul_f32 v[170:171], v[26:27], v[170:171] op_sel_hi:[0,1]
	v_pk_mul_f32 v[212:213], v[26:27], v[212:213] op_sel_hi:[0,1]
	v_pk_mul_f32 v[180:181], v[26:27], v[180:181] op_sel_hi:[0,1]
	v_pk_mul_f32 v[214:215], v[26:27], v[214:215] op_sel_hi:[0,1]
	v_pk_mul_f32 v[182:183], v[26:27], v[182:183] op_sel_hi:[0,1]
	v_pk_mul_f32 v[218:219], v[26:27], v[218:219] op_sel_hi:[0,1]
	v_pk_mul_f32 v[186:187], v[26:27], v[186:187] op_sel_hi:[0,1]
	v_pk_mul_f32 v[220:221], v[26:27], v[220:221] op_sel_hi:[0,1]
	v_pk_mul_f32 v[188:189], v[26:27], v[188:189] op_sel_hi:[0,1]
	v_pk_mul_f32 v[224:225], v[26:27], v[224:225] op_sel_hi:[0,1]
	v_pk_mul_f32 v[194:195], v[26:27], v[194:195] op_sel_hi:[0,1]
	v_pk_mul_f32 v[226:227], v[26:27], v[226:227] op_sel_hi:[0,1]
	v_pk_mul_f32 v[196:197], v[26:27], v[196:197] op_sel_hi:[0,1]
	v_pk_fma_f32 v[232:233], v[38:39], v[66:67], v[30:31]
	v_pk_fma_f32 v[198:199], v[36:37], v[198:199], v[28:29]
	v_pk_fma_f32 v[234:235], v[42:43], v[68:69], v[34:35]
	v_pk_fma_f32 v[200:201], v[40:41], v[200:201], v[32:33]
	v_pk_mul_f32 v[210:211], v[26:27], v[210:211] op_sel_hi:[0,1]
	v_pk_mul_f32 v[172:173], v[26:27], v[172:173] op_sel_hi:[0,1]
	v_pk_mul_f32 v[216:217], v[26:27], v[216:217] op_sel_hi:[0,1]
	v_pk_mul_f32 v[184:185], v[26:27], v[184:185] op_sel_hi:[0,1]
	v_pk_mul_f32 v[222:223], v[26:27], v[222:223] op_sel_hi:[0,1]
	v_pk_mul_f32 v[190:191], v[26:27], v[190:191] op_sel_hi:[0,1]
	v_pk_mul_f32 v[228:229], v[26:27], v[228:229] op_sel_hi:[0,1]
	v_pk_mul_f32 v[230:231], v[26:27], v[20:21] op_sel_hi:[0,1]
	v_pk_fma_f32 v[236:237], v[56:57], v[70:71], v[48:49]
	v_pk_fma_f32 v[202:203], v[54:55], v[202:203], v[46:47]
	v_pk_fma_f32 v[70:71], v[60:61], v[72:73], v[52:53]
	v_pk_fma_f32 v[72:73], v[58:59], v[204:205], v[50:51]
	v_pk_fma_f32 v[66:67], v[64:65], v[168:169], v[18:19]
	v_pk_fma_f32 v[68:69], v[62:63], v[206:207], v[16:17]
	v_pk_fma_f32 v[62:63], v[86:87], v[170:171], v[82:83]
	v_pk_fma_f32 v[64:65], v[84:85], v[208:209], v[80:81]
	v_pk_fma_f32 v[54:55], v[102:103], v[180:181], v[94:95]
	v_pk_fma_f32 v[56:57], v[100:101], v[212:213], v[92:93]
	v_pk_fma_f32 v[50:51], v[114:115], v[182:183], v[106:107]
	v_pk_fma_f32 v[52:53], v[112:113], v[214:215], v[104:105]
	v_pk_fma_f32 v[40:41], v[130:131], v[186:187], v[122:123]
	v_pk_fma_f32 v[42:43], v[128:129], v[218:219], v[120:121]
	v_pk_fma_f32 v[36:37], v[134:135], v[188:189], v[126:127]
	v_pk_fma_f32 v[38:39], v[132:133], v[220:221], v[124:125]
	v_pk_fma_f32 v[28:29], v[150:151], v[194:195], v[142:143]
	v_pk_fma_f32 v[30:31], v[148:149], v[224:225], v[140:141]
	v_pk_fma_f32 v[20:21], v[162:163], v[196:197], v[154:155]
	v_pk_fma_f32 v[26:27], v[160:161], v[226:227], v[152:153]
	v_pk_mul_f32 v[80:81], v[232:233], v[232:233]
	v_pk_mul_f32 v[82:83], v[198:199], v[198:199]
	v_pk_mul_f32 v[84:85], v[234:235], v[234:235]
	v_pk_mul_f32 v[86:87], v[200:201], v[200:201]
	v_pk_fma_f32 v[58:59], v[98:99], v[172:173], v[90:91]
	v_pk_fma_f32 v[60:61], v[96:97], v[210:211], v[88:89]
	v_pk_fma_f32 v[46:47], v[118:119], v[184:185], v[110:111]
	v_pk_fma_f32 v[48:49], v[116:117], v[216:217], v[108:109]
	v_pk_mul_f32 v[90:91], v[66:67], v[66:67]
	v_pk_mul_f32 v[92:93], v[68:69], v[68:69]
	v_mul_f32_e32 v94, v65, v65
	v_mul_f32_e32 v96, v63, v63
	v_pk_mul_f32 v[98:99], v[54:55], v[54:55]
; __device__ __forceinline__ unsigned cvt_pk_bf16(float lo, float hi) { unsigned r; asm volatile("v_cvt_pk_bf16_f32 %0, %1, %2" : "=v"(r) : "v"(lo), "v"(hi)); return r; }
; __device__ __forceinline__ float bf_lo(unsigned w) { return __uint_as_float(w << 16); }
; __device__ __forceinline__ float bf_hi(unsigned w) { return __uint_as_float(w & 0xffff0000u); }
; __device__ __forceinline__ float wave_sum(float v) {
; #pragma unroll
;     for (int o = 1; o < 64; o <<= 1) v += __shfl_xor(v, o);
;     return v;
; __device__ __forceinline__ void phase_mid(const Params& p, int gw, int NGW, int lane) {
;     ...
;         for (int j = 0; j < 16; ++j) { const u32x2 mw = mr[64 * j]; const f32x4 mo = {bf_lo(mw.x), bf_hi(mw.x), bf_lo(mw.y), bf_hi(mw.y)}; h[j] = xr[64 * j] + mo * r1 * g1p[64 * j]; ss += (h[j][0] * h[j][0] + h[j][1] * h[j][1]) + (h[j][2] * h[j][2] + h[j][3] * h[j][3]); }
;         const float r2 = rsqrtf(wave_sum(ss) * (1.f / DM) + EPSN);
;         u32x2* ho = (u32x2*)(H1 + (size_t)row * DM) + lane; u32x2* co = (u32x2*)(Cb + (size_t)row * DM) + lane;
;         asm volatile("" : "+v"(ho), "+v"(co));
; #pragma unroll
;         for (int j = 0; j < 16; ++j) { { u32x2 hw; hw.x = cvt_pk_bf16(h[j][0], h[j][1]); hw.y = cvt_pk_bf16(h[j][2], h[j][3]); ho[64 * j] = hw; } const f32x4 c = h[j] * r2 * g2p[64 * j]; u32x2 w; w.x = cvt_pk_bf16(c[0], c[1]); w.y = cvt_pk_bf16(c[2], c[3]); co[64 * j] = w; }
	v_pk_mul_f32 v[100:101], v[56:57], v[56:57]
	v_mul_f32_e32 v102, v53, v53
	v_mul_f32_e32 v104, v51, v51
	v_pk_mul_f32 v[106:107], v[40:41], v[40:41]
	v_pk_mul_f32 v[108:109], v[42:43], v[42:43]
	v_mul_f32_e32 v110, v39, v39
	v_mul_f32_e32 v112, v37, v37
	v_pk_mul_f32 v[114:115], v[28:29], v[28:29]
	v_pk_mul_f32 v[116:117], v[30:31], v[30:31]
	v_mul_f32_e32 v118, v27, v27
	v_mul_f32_e32 v120, v21, v21
	v_cvt_pk_bf16_f32 v122, v198, v199
	v_cvt_pk_bf16_f32 v123, v232, v233
	v_pk_mov_b32 v[124:125], v[82:83], v[80:81] op_sel:[1,0]
	v_mov_b32_e32 v83, v81
	v_pk_mov_b32 v[80:81], v[86:87], v[84:85] op_sel:[1,0]
	v_mov_b32_e32 v87, v85
	flat_store_dwordx2 v[24:25], v[122:123]
	v_pk_mov_b32 v[126:127], v[92:93], v[90:91] op_sel:[1,0]
	v_mov_b32_e32 v93, v91
	v_pk_fma_f32 v[90:91], v[64:65], v[64:65], v[94:95] op_sel_hi:[1,1,0]
	v_pk_fma_f32 v[94:95], v[62:63], v[62:63], v[96:97] op_sel_hi:[1,1,0]
	v_pk_mov_b32 v[96:97], v[100:101], v[98:99] op_sel:[1,0]
	v_mov_b32_e32 v101, v99
	v_pk_fma_f32 v[98:99], v[52:53], v[52:53], v[102:103] op_sel_hi:[1,1,0]
	v_pk_fma_f32 v[102:103], v[50:51], v[50:51], v[104:105] op_sel_hi:[1,1,0]
	v_pk_mov_b32 v[104:105], v[108:109], v[106:107] op_sel:[1,0]
	v_mov_b32_e32 v109, v107
	v_pk_fma_f32 v[106:107], v[38:39], v[38:39], v[110:111] op_sel_hi:[1,1,0]
	v_pk_fma_f32 v[110:111], v[36:37], v[36:37], v[112:113] op_sel_hi:[1,1,0]
	v_pk_mov_b32 v[112:113], v[116:117], v[114:115] op_sel:[1,0]
	v_mov_b32_e32 v117, v115
	v_pk_fma_f32 v[114:115], v[26:27], v[26:27], v[118:119] op_sel_hi:[1,1,0]
	v_pk_fma_f32 v[118:119], v[20:21], v[20:21], v[120:121] op_sel_hi:[1,1,0]
	v_pk_add_f32 v[120:121], v[124:125], v[82:83]
	v_pk_add_f32 v[86:87], v[80:81], v[86:87]
	flat_load_dwordx4 v[80:83], v[14:15]
	v_mul_f32_e32 v44, v203, v203
	v_mul_f32_e32 v88, v237, v237
	v_mul_f32_e32 v128, v72, v72
	v_mul_f32_e32 v129, v73, v73
	v_mul_f32_e32 v130, v70, v70
	v_mul_f32_e32 v131, v71, v71
	v_pk_fma_f32 v[84:85], v[202:203], v[202:203], v[44:45] op_sel_hi:[1,1,0]
	v_pk_fma_f32 v[88:89], v[236:237], v[236:237], v[88:89] op_sel_hi:[1,1,0]
	v_pk_add_f32 v[96:97], v[96:97], v[100:101]
	v_pk_add_f32 v[100:101], v[104:105], v[108:109]
	v_pk_add_f32 v[108:109], v[120:121], v[120:121] op_sel:[0,1] op_sel_hi:[1,0]
	v_pk_add_f32 v[86:87], v[86:87], v[86:87] op_sel:[0,1] op_sel_hi:[1,0]
	v_mov_b32_e32 v85, v130
	v_mov_b32_e32 v89, v131
	v_mov_b32_e32 v109, v128
	v_mov_b32_e32 v87, v129
	v_pk_add_f32 v[84:85], v[84:85], v[88:89]
	v_pk_add_f32 v[86:87], v[108:109], v[86:87]
	v_pk_add_f32 v[92:93], v[126:127], v[92:93]
	v_pk_add_f32 v[84:85], v[86:87], v[84:85]
	v_mul_f32_e32 v132, v60, v60
	v_mul_f32_e32 v133, v61, v61
	v_mul_f32_e32 v134, v58, v58
	v_mul_f32_e32 v135, v59, v59
	v_pk_add_f32 v[88:89], v[92:93], v[92:93] op_sel:[0,1] op_sel_hi:[1,0]
	v_pk_add_f32 v[84:85], v[84:85], v[84:85] op_sel:[0,1] op_sel_hi:[1,0]
	v_mov_b32_e32 v91, v134
	v_mov_b32_e32 v95, v135
	v_mov_b32_e32 v89, v133
	v_mov_b32_e32 v85, v132
	v_pk_add_f32 v[90:91], v[90:91], v[94:95]
	v_pk_add_f32 v[84:85], v[84:85], v[88:89]
	v_pk_fma_f32 v[32:33], v[146:147], v[190:191], v[138:139]
	v_pk_add_f32 v[84:85], v[84:85], v[90:91]
	v_pk_fma_f32 v[34:35], v[144:145], v[222:223], v[136:137]
	v_mul_f32_e32 v136, v48, v48
	v_mul_f32_e32 v137, v49, v49
	v_mul_f32_e32 v138, v46, v46
	v_mul_f32_e32 v139, v47, v47
	v_pk_add_f32 v[92:93], v[96:97], v[96:97] op_sel:[0,1] op_sel_hi:[1,0]
	v_pk_add_f32 v[84:85], v[84:85], v[84:85] op_sel:[0,1] op_sel_hi:[1,0]
	v_mov_b32_e32 v99, v138
	v_mov_b32_e32 v103, v139
	v_mov_b32_e32 v93, v137
	v_mov_b32_e32 v85, v136
	v_pk_add_f32 v[94:95], v[98:99], v[102:103]
	v_pk_add_f32 v[84:85], v[84:85], v[92:93]
	v_mul_f32_e32 v140, v34, v34
	v_pk_add_f32 v[84:85], v[84:85], v[94:95]
	v_mul_f32_e32 v141, v35, v35
	v_mul_f32_e32 v142, v32, v32
	v_mul_f32_e32 v143, v33, v33
	v_pk_add_f32 v[96:97], v[100:101], v[100:101] op_sel:[0,1] op_sel_hi:[1,0]
	v_pk_add_f32 v[84:85], v[84:85], v[84:85] op_sel:[0,1] op_sel_hi:[1,0]
	v_mov_b32_e32 v107, v142
	v_mov_b32_e32 v111, v143
	v_mov_b32_e32 v97, v141
	v_mov_b32_e32 v85, v140
	v_pk_add_f32 v[98:99], v[106:107], v[110:111]
	v_pk_add_f32 v[84:85], v[84:85], v[96:97]
	v_pk_fma_f32 v[16:17], v[166:167], v[230:231], v[158:159]
	v_pk_fma_f32 v[18:19], v[164:165], v[228:229], v[156:157]
	v_pk_add_f32 v[104:105], v[112:113], v[116:117]
	v_pk_add_f32 v[84:85], v[84:85], v[98:99]
	v_mul_f32_e32 v144, v18, v18
	v_mul_f32_e32 v145, v19, v19
	v_mul_f32_e32 v146, v16, v16
	v_mul_f32_e32 v147, v17, v17
	v_pk_add_f32 v[100:101], v[104:105], v[104:105] op_sel:[0,1] op_sel_hi:[1,0]
	v_pk_add_f32 v[84:85], v[84:85], v[84:85] op_sel:[0,1] op_sel_hi:[1,0]
	v_mov_b32_e32 v115, v146
	v_mov_b32_e32 v119, v147
	v_mov_b32_e32 v101, v145
	v_mov_b32_e32 v85, v144
	v_pk_add_f32 v[102:103], v[114:115], v[118:119]
	v_pk_add_f32 v[84:85], v[84:85], v[100:101]
	s_nop 0
	v_pk_add_f32 v[84:85], v[84:85], v[102:103]
	s_nop 0
	v_add_f32_e32 v44, v84, v85
	ds_bpermute_b32 v84, v45, v44
	s_waitcnt lgkmcnt(0)
	v_add_f32_e32 v44, v44, v84
	ds_bpermute_b32 v84, v74, v44
	s_waitcnt lgkmcnt(0)
	v_add_f32_e32 v44, v44, v84
	ds_bpermute_b32 v84, v75, v44
	s_waitcnt lgkmcnt(0)
	v_add_f32_e32 v44, v44, v84
	ds_bpermute_b32 v84, v76, v44
	s_waitcnt lgkmcnt(0)
	v_add_f32_e32 v44, v44, v84
	ds_bpermute_b32 v84, v77, v44
	s_waitcnt lgkmcnt(0)
	v_add_f32_e32 v44, v44, v84
	ds_bpermute_b32 v84, v78, v44
	s_waitcnt lgkmcnt(0)
	v_add_f32_e32 v44, v44, v84
	v_fmamk_f32 v44, v44, 0x39800000, v79
	v_mul_f32_e32 v84, 0x4b800000, v44
	v_cmp_gt_f32_e32 vcc, s8, v44
	s_nop 1
	v_cndmask_b32_e32 v44, v44, v84, vcc
	v_rsq_f32_e32 v44, v44
	s_nop 0
	v_mul_f32_e32 v84, 0x45800000, v44
	v_cndmask_b32_e32 v44, v44, v84, vcc
	v_pk_mul_f32 v[84:85], v[198:199], v[44:45] op_sel_hi:[1,0]
	v_pk_mul_f32 v[86:87], v[232:233], v[44:45] op_sel_hi:[1,0]
	s_waitcnt vmcnt(0)
; __device__ __forceinline__ unsigned cvt_pk_bf16(float lo, float hi) { unsigned r; asm volatile("v_cvt_pk_bf16_f32 %0, %1, %2" : "=v"(r) : "v"(lo), "v"(hi)); return r; }
; __device__ __forceinline__ void phase_mid(const Params& p, int gw, int NGW, int lane) {
;     ...
;         const float r2 = rsqrtf(wave_sum(ss) * (1.f / DM) + EPSN);
;         u32x2* ho = (u32x2*)(H1 + (size_t)row * DM) + lane; u32x2* co = (u32x2*)(Cb + (size_t)row * DM) + lane;
;         asm volatile("" : "+v"(ho), "+v"(co));
; #pragma unroll
;         for (int j = 0; j < 16; ++j) { { u32x2 hw; hw.x = cvt_pk_bf16(h[j][0], h[j][1]); hw.y = cvt_pk_bf16(h[j][2], h[j][3]); ho[64 * j] = hw; } const f32x4 c = h[j] * r2 * g2p[64 * j]; u32x2 w; w.x = cvt_pk_bf16(c[0], c[1]); w.y = cvt_pk_bf16(c[2], c[3]); co[64 * j] = w; }
	v_pk_mul_f32 v[80:81], v[80:81], v[84:85]
	v_pk_mul_f32 v[82:83], v[82:83], v[86:87]
	v_cvt_pk_bf16_f32 v80, v80, v81
	v_pk_mul_f32 v[84:85], v[200:201], v[44:45] op_sel_hi:[1,0]
	v_cvt_pk_bf16_f32 v81, v82, v83
	flat_store_dwordx2 v[22:23], v[80:81]
	v_cvt_pk_bf16_f32 v80, v200, v201
	v_cvt_pk_bf16_f32 v81, v234, v235
	flat_store_dwordx2 v[24:25], v[80:81] offset:512
	flat_load_dwordx4 v[80:83], v[14:15] offset:1024
	v_pk_mul_f32 v[86:87], v[234:235], v[44:45] op_sel_hi:[1,0]
	s_waitcnt vmcnt(0) lgkmcnt(0)
	v_pk_mul_f32 v[80:81], v[80:81], v[84:85]
	v_pk_mul_f32 v[82:83], v[82:83], v[86:87]
	v_cvt_pk_bf16_f32 v80, v80, v81
	v_pk_mul_f32 v[84:85], v[202:203], v[44:45] op_sel_hi:[1,0]
	v_cvt_pk_bf16_f32 v81, v82, v83
	flat_store_dwordx2 v[22:23], v[80:81] offset:512
	v_cvt_pk_bf16_f32 v80, v202, v203
	v_cvt_pk_bf16_f32 v81, v236, v237
	flat_store_dwordx2 v[24:25], v[80:81] offset:1024
	flat_load_dwordx4 v[80:83], v[14:15] offset:2048
	v_pk_mul_f32 v[86:87], v[236:237], v[44:45] op_sel_hi:[1,0]
	s_waitcnt vmcnt(0) lgkmcnt(0)
	v_pk_mul_f32 v[80:81], v[80:81], v[84:85]
	v_pk_mul_f32 v[82:83], v[82:83], v[86:87]
	v_cvt_pk_bf16_f32 v80, v80, v81
	v_add_co_u32_e32 v84, vcc, s9, v14
	v_cvt_pk_bf16_f32 v81, v82, v83
	flat_store_dwordx2 v[22:23], v[80:81] offset:1024
	v_cvt_pk_bf16_f32 v80, v72, v73
	v_cvt_pk_bf16_f32 v81, v70, v71
	flat_store_dwordx2 v[24:25], v[80:81] offset:1536
	flat_load_dwordx4 v[80:83], v[14:15] offset:3072
	v_pk_mul_f32 v[72:73], v[72:73], v[44:45] op_sel_hi:[1,0]
	v_pk_mul_f32 v[70:71], v[70:71], v[44:45] op_sel_hi:[1,0]
	v_addc_co_u32_e32 v85, vcc, 0, v15, vcc
	s_waitcnt vmcnt(0) lgkmcnt(0)
	v_pk_mul_f32 v[70:71], v[70:71], v[82:83]
	v_pk_mul_f32 v[72:73], v[72:73], v[80:81]
	s_nop 0
	v_cvt_pk_bf16_f32 v72, v72, v73
	v_cvt_pk_bf16_f32 v73, v70, v71
	flat_store_dwordx2 v[22:23], v[72:73] offset:1536
	v_cvt_pk_bf16_f32 v70, v68, v69
	v_cvt_pk_bf16_f32 v71, v66, v67
	flat_store_dwordx2 v[24:25], v[70:71] offset:2048
	flat_load_dwordx4 v[70:73], v[84:85]
	v_pk_mul_f32 v[68:69], v[68:69], v[44:45] op_sel_hi:[1,0]
	v_pk_mul_f32 v[66:67], v[66:67], v[44:45] op_sel_hi:[1,0]
	s_waitcnt vmcnt(0) lgkmcnt(0)
	v_pk_mul_f32 v[68:69], v[68:69], v[70:71]
	v_pk_mul_f32 v[66:67], v[66:67], v[72:73]
	v_cvt_pk_bf16_f32 v68, v68, v69
	s_nop 0
	v_cvt_pk_bf16_f32 v69, v66, v67
	flat_store_dwordx2 v[22:23], v[68:69] offset:2048
	v_cvt_pk_bf16_f32 v66, v64, v65
	v_cvt_pk_bf16_f32 v67, v62, v63
	flat_store_dwordx2 v[24:25], v[66:67] offset:2560
	flat_load_dwordx4 v[66:69], v[84:85] offset:1024
	v_pk_mul_f32 v[64:65], v[64:65], v[44:45] op_sel_hi:[1,0]
	v_pk_mul_f32 v[62:63], v[62:63], v[44:45] op_sel_hi:[1,0]
	s_waitcnt vmcnt(0) lgkmcnt(0)
	v_pk_mul_f32 v[64:65], v[64:65], v[66:67]
	v_pk_mul_f32 v[62:63], v[62:63], v[68:69]
	v_cvt_pk_bf16_f32 v64, v64, v65
	s_nop 0
	v_cvt_pk_bf16_f32 v65, v62, v63
	flat_store_dwordx2 v[22:23], v[64:65] offset:2560
	v_cvt_pk_bf16_f32 v62, v60, v61
	v_cvt_pk_bf16_f32 v63, v58, v59
	flat_store_dwordx2 v[24:25], v[62:63] offset:3072
	flat_load_dwordx4 v[62:65], v[84:85] offset:2048
	v_pk_mul_f32 v[60:61], v[60:61], v[44:45] op_sel_hi:[1,0]
	v_pk_mul_f32 v[58:59], v[58:59], v[44:45] op_sel_hi:[1,0]
	s_waitcnt vmcnt(0) lgkmcnt(0)
	v_pk_mul_f32 v[60:61], v[60:61], v[62:63]
	v_pk_mul_f32 v[58:59], v[58:59], v[64:65]
	v_cvt_pk_bf16_f32 v60, v60, v61
	v_add_co_u32_e32 v62, vcc, s3, v14
	v_cvt_pk_bf16_f32 v61, v58, v59
	flat_store_dwordx2 v[22:23], v[60:61] offset:3072
	v_cvt_pk_bf16_f32 v58, v56, v57
	v_cvt_pk_bf16_f32 v59, v54, v55
	flat_store_dwordx2 v[24:25], v[58:59] offset:3584
	flat_load_dwordx4 v[58:61], v[84:85] offset:3072
	v_addc_co_u32_e32 v63, vcc, 0, v15, vcc
	v_add_co_u32_e32 v64, vcc, s9, v24
	v_pk_mul_f32 v[54:55], v[54:55], v[44:45] op_sel_hi:[1,0]
	s_nop 0
	v_addc_co_u32_e32 v65, vcc, 0, v25, vcc
	v_pk_mul_f32 v[24:25], v[56:57], v[44:45] op_sel_hi:[1,0]
	s_waitcnt vmcnt(0) lgkmcnt(0)
	v_pk_mul_f32 v[54:55], v[54:55], v[60:61]
	v_pk_mul_f32 v[24:25], v[24:25], v[58:59]
	v_add_co_u32_e32 v58, vcc, s9, v22
	v_cvt_pk_bf16_f32 v24, v24, v25
	v_cvt_pk_bf16_f32 v25, v54, v55
	flat_store_dwordx2 v[22:23], v[24:25] offset:3584
	v_cvt_pk_bf16_f32 v24, v52, v53
	v_cvt_pk_bf16_f32 v25, v50, v51
	flat_store_dwordx2 v[64:65], v[24:25]
	flat_load_dwordx4 v[54:57], v[62:63]
	v_addc_co_u32_e32 v59, vcc, 0, v23, vcc
	v_pk_mul_f32 v[22:23], v[52:53], v[44:45] op_sel_hi:[1,0]
	v_pk_mul_f32 v[24:25], v[50:51], v[44:45] op_sel_hi:[1,0]
	v_add_co_u32_e32 v14, vcc, s16, v14
	s_waitcnt vmcnt(0) lgkmcnt(0)
; __device__ __forceinline__ unsigned cvt_pk_bf16(float lo, float hi) { unsigned r; asm volatile("v_cvt_pk_bf16_f32 %0, %1, %2" : "=v"(r) : "v"(lo), "v"(hi)); return r; }
; __device__ __forceinline__ void phase_mid(const Params& p, int gw, int NGW, int lane) {
;     ...
;         for (int j = 0; j < 16; ++j) { { u32x2 hw; hw.x = cvt_pk_bf16(h[j][0], h[j][1]); hw.y = cvt_pk_bf16(h[j][2], h[j][3]); ho[64 * j] = hw; } const f32x4 c = h[j] * r2 * g2p[64 * j]; u32x2 w; w.x = cvt_pk_bf16(c[0], c[1]); w.y = cvt_pk_bf16(c[2], c[3]); co[64 * j] = w; }
	v_pk_mul_f32 v[22:23], v[22:23], v[54:55]
	v_pk_mul_f32 v[24:25], v[24:25], v[56:57]
	v_cvt_pk_bf16_f32 v22, v22, v23
	v_addc_co_u32_e32 v15, vcc, 0, v15, vcc
	v_cvt_pk_bf16_f32 v23, v24, v25
	flat_store_dwordx2 v[58:59], v[22:23]
	v_cvt_pk_bf16_f32 v22, v48, v49
	v_cvt_pk_bf16_f32 v23, v46, v47
	flat_store_dwordx2 v[64:65], v[22:23] offset:512
	flat_load_dwordx4 v[22:25], v[62:63] offset:1024
	v_pk_mul_f32 v[48:49], v[48:49], v[44:45] op_sel_hi:[1,0]
	v_pk_mul_f32 v[46:47], v[46:47], v[44:45] op_sel_hi:[1,0]
	s_waitcnt vmcnt(0) lgkmcnt(0)
	v_pk_mul_f32 v[22:23], v[48:49], v[22:23]
	v_pk_mul_f32 v[24:25], v[46:47], v[24:25]
	v_cvt_pk_bf16_f32 v22, v22, v23
	s_nop 0
	v_cvt_pk_bf16_f32 v23, v24, v25
	flat_store_dwordx2 v[58:59], v[22:23] offset:512
	v_cvt_pk_bf16_f32 v22, v42, v43
	v_cvt_pk_bf16_f32 v23, v40, v41
	flat_store_dwordx2 v[64:65], v[22:23] offset:1024
	flat_load_dwordx4 v[22:25], v[62:63] offset:2048
	v_pk_mul_f32 v[42:43], v[42:43], v[44:45] op_sel_hi:[1,0]
	v_pk_mul_f32 v[40:41], v[40:41], v[44:45] op_sel_hi:[1,0]
	s_waitcnt vmcnt(0) lgkmcnt(0)
	v_pk_mul_f32 v[22:23], v[42:43], v[22:23]
	v_pk_mul_f32 v[24:25], v[40:41], v[24:25]
	v_cvt_pk_bf16_f32 v22, v22, v23
	s_nop 0
	v_cvt_pk_bf16_f32 v23, v24, v25
	flat_store_dwordx2 v[58:59], v[22:23] offset:1024
	v_cvt_pk_bf16_f32 v22, v38, v39
	v_cvt_pk_bf16_f32 v23, v36, v37
	flat_store_dwordx2 v[64:65], v[22:23] offset:1536
	flat_load_dwordx4 v[22:25], v[62:63] offset:3072
	v_pk_mul_f32 v[38:39], v[38:39], v[44:45] op_sel_hi:[1,0]
	v_pk_mul_f32 v[36:37], v[36:37], v[44:45] op_sel_hi:[1,0]
	s_waitcnt vmcnt(0) lgkmcnt(0)
	v_pk_mul_f32 v[22:23], v[38:39], v[22:23]
	v_pk_mul_f32 v[24:25], v[36:37], v[24:25]
	v_cvt_pk_bf16_f32 v22, v22, v23
	s_nop 0
	v_cvt_pk_bf16_f32 v23, v24, v25
	flat_store_dwordx2 v[58:59], v[22:23] offset:1536
	v_cvt_pk_bf16_f32 v22, v34, v35
	v_cvt_pk_bf16_f32 v23, v32, v33
	flat_store_dwordx2 v[64:65], v[22:23] offset:2048
	flat_load_dwordx4 v[22:25], v[14:15]
	v_pk_mul_f32 v[34:35], v[34:35], v[44:45] op_sel_hi:[1,0]
	v_pk_mul_f32 v[32:33], v[32:33], v[44:45] op_sel_hi:[1,0]
	s_waitcnt vmcnt(0) lgkmcnt(0)
	v_pk_mul_f32 v[22:23], v[34:35], v[22:23]
	v_pk_mul_f32 v[24:25], v[32:33], v[24:25]
	v_cvt_pk_bf16_f32 v22, v22, v23
	s_nop 0
	v_cvt_pk_bf16_f32 v23, v24, v25
	flat_store_dwordx2 v[58:59], v[22:23] offset:2048
	v_cvt_pk_bf16_f32 v22, v30, v31
	v_cvt_pk_bf16_f32 v23, v28, v29
	flat_store_dwordx2 v[64:65], v[22:23] offset:2560
	flat_load_dwordx4 v[22:25], v[14:15] offset:1024
	v_pk_mul_f32 v[30:31], v[30:31], v[44:45] op_sel_hi:[1,0]
	v_pk_mul_f32 v[28:29], v[28:29], v[44:45] op_sel_hi:[1,0]
	s_waitcnt vmcnt(0) lgkmcnt(0)
	v_pk_mul_f32 v[22:23], v[30:31], v[22:23]
	v_pk_mul_f32 v[24:25], v[28:29], v[24:25]
	v_cvt_pk_bf16_f32 v22, v22, v23
	s_nop 0
	v_cvt_pk_bf16_f32 v23, v24, v25
	flat_store_dwordx2 v[58:59], v[22:23] offset:2560
	v_cvt_pk_bf16_f32 v22, v26, v27
	v_cvt_pk_bf16_f32 v23, v20, v21
	flat_store_dwordx2 v[64:65], v[22:23] offset:3072
	flat_load_dwordx4 v[22:25], v[14:15] offset:2048
	v_pk_mul_f32 v[26:27], v[26:27], v[44:45] op_sel_hi:[1,0]
	v_pk_mul_f32 v[20:21], v[20:21], v[44:45] op_sel_hi:[1,0]
	s_waitcnt vmcnt(0) lgkmcnt(0)
	v_pk_mul_f32 v[22:23], v[26:27], v[22:23]
	v_pk_mul_f32 v[20:21], v[20:21], v[24:25]
	v_cvt_pk_bf16_f32 v22, v22, v23
	s_nop 0
	v_cvt_pk_bf16_f32 v23, v20, v21
	flat_store_dwordx2 v[58:59], v[22:23] offset:3072
	v_cvt_pk_bf16_f32 v20, v18, v19
	v_cvt_pk_bf16_f32 v21, v16, v17
	flat_store_dwordx2 v[64:65], v[20:21] offset:3584
	flat_load_dwordx4 v[20:23], v[14:15] offset:3072
	v_pk_mul_f32 v[14:15], v[18:19], v[44:45] op_sel_hi:[1,0]
	v_pk_mul_f32 v[16:17], v[16:17], v[44:45] op_sel_hi:[1,0]
	s_waitcnt vmcnt(0) lgkmcnt(0)
	v_pk_mul_f32 v[14:15], v[14:15], v[20:21]
	v_pk_mul_f32 v[16:17], v[16:17], v[22:23]
	v_cvt_pk_bf16_f32 v14, v14, v15
	s_nop 0
	v_cvt_pk_bf16_f32 v15, v16, v17
	flat_store_dwordx2 v[58:59], v[14:15] offset:3584
	s_cbranch_scc1 .LBB0_711
